# adds: duplicate L2 write-back and duplicate L1 invalidate around the cooperative grid sync removed
# speedup vs baseline: 1.0217x; 1.0065x over previous
.LBB0_73:
	s_waitcnt vmcnt(0)
	v_cmp_eq_u32_e64 s[64:65], 0, v247
	s_waitcnt lgkmcnt(0)
	s_barrier
	s_and_saveexec_b64 s[4:5], s[64:65]
	s_cbranch_execz .LBB0_75
	s_waitcnt vmcnt(0)
	s_waitcnt vmcnt(0)

.LBB0_84:
.LBB0_85:
	s_or_b64 exec, exec, s[4:5]
	s_barrier
	s_and_saveexec_b64 s[0:1], s[64:65]
	s_cbranch_execz .LBB0_87
	s_waitcnt vmcnt(0)
	buffer_inv sc1
	s_waitcnt vmcnt(0)
